# finish phase: 12 (pass 1) / 15 (pass 2) block loads in flight per wave instead of one block's 3-5 loads waited on immediately; on top of v33
# baseline (speedup 1.0000x reference)
; __device__ __forceinline__ void finish_phase(CParams& p, int layer) {
;     ...
;     for (int tr = blockIdx.x * 4 + wave; tr < MT / 16; tr += gridDim.x * 4) {
;         const size_t base = (size_t)tr * 64 * 512 + lane * 8;
; #pragma unroll 1
;         for (int g = 0; g < 4; ++g) {
;             float ss = 0.f;
; #pragma unroll 4
;             for (int kk = 0; kk < 16; ++kk) {
;                 const size_t off = base + (size_t)(g * 16 + kk) * 512;
;                 const u32x4 a = *(const u32x4*)(yf + off), bq = *(const u32x4*)(yb + off), zq = *(const u32x4*)(z + off);
;                 const unsigned aw[4] = {a.x, a.y, a.z, a.w}, bw[4] = {bq.x, bq.y, bq.z, bq.w}, zw[4] = {zq.x, zq.y, zq.z, zq.w};
; #pragma unroll
;                 for (int k = 0; k < 4; ++k) {
;                     const float v0 = (__uint_as_float(aw[k] << 16) + __uint_as_float(bw[k] << 16)) * __uint_as_float(zw[k] << 16);
;                     const float v1 = (__uint_as_float(aw[k] & 0xffff0000u) + __uint_as_float(bw[k] & 0xffff0000u)) * __uint_as_float(zw[k] & 0xffff0000u);
;                     ss += v0 * v0 + v1 * v1;
;                 }
;             }
.LBB0_506:
	v_lshl_add_u64 v[18:19], v[6:7], 0, s[4:5]
	v_add_co_u32_e32 v26, vcc, 0x2700000, v18
	s_add_u32 s4, s4, 0x1000
	s_nop 0
	v_addc_co_u32_e32 v27, vcc, 0, v19, vcc
	v_add_co_u32_e32 v28, vcc, 0x6900000, v18
	global_load_dwordx4 v[10:13], v[26:27], off
	s_nop 0
	v_addc_co_u32_e32 v29, vcc, 0, v19, vcc
	v_add_co_u32_e32 v18, vcc, 0xab00000, v18
	global_load_dwordx4 v[14:17], v[28:29], off
	s_nop 0
	v_addc_co_u32_e32 v19, vcc, 0, v19, vcc
	global_load_dwordx4 v[22:25], v[18:19], off
	global_load_dwordx4 v[48:51], v[26:27], off offset:1024
	global_load_dwordx4 v[52:55], v[28:29], off offset:1024
	global_load_dwordx4 v[56:59], v[18:19], off offset:1024
	global_load_dwordx4 v[60:63], v[26:27], off offset:2048
	global_load_dwordx4 v[64:67], v[28:29], off offset:2048
	global_load_dwordx4 v[68:71], v[18:19], off offset:2048
	global_load_dwordx4 v[72:75], v[26:27], off offset:3072
	global_load_dwordx4 v[76:79], v[28:29], off offset:3072
	global_load_dwordx4 v[80:83], v[18:19], off offset:3072
	s_addc_u32 s5, s5, 0
	s_cmpk_eq_i32 s4, 0x4000
	s_waitcnt vmcnt(11)
	v_lshlrev_b32_e32 v30, 16, v10
	v_and_b32_e32 v31, 0xffff0000, v10
	s_waitcnt vmcnt(10)
	v_lshlrev_b32_e32 v32, 16, v14
	v_and_b32_e32 v33, 0xffff0000, v14
	v_pk_add_f32 v[30:31], v[30:31], v[32:33]
	s_waitcnt vmcnt(9)
	v_lshlrev_b32_e32 v32, 16, v22
	v_and_b32_e32 v33, 0xffff0000, v22
	v_pk_mul_f32 v[30:31], v[30:31], v[32:33]
	v_lshlrev_b32_e32 v33, 16, v16
	v_pk_mul_f32 v[30:31], v[30:31], v[30:31]
	v_lshlrev_b32_e32 v32, 16, v15
	v_add_f32_e32 v10, v30, v31
	v_lshlrev_b32_e32 v31, 16, v12
	v_lshlrev_b32_e32 v30, 16, v11
	v_pk_add_f32 v[30:31], v[30:31], v[32:33]
	v_lshlrev_b32_e32 v33, 16, v24
	v_lshlrev_b32_e32 v32, 16, v23
	v_add_f32_e32 v1, v1, v10
	v_pk_mul_f32 v[30:31], v[30:31], v[32:33]
	v_and_b32_e32 v33, 0xffff0000, v12
	v_and_b32_e32 v32, 0xffff0000, v11
	v_and_b32_e32 v11, 0xffff0000, v16
	v_and_b32_e32 v10, 0xffff0000, v15
	v_pk_add_f32 v[10:11], v[32:33], v[10:11]
	v_and_b32_e32 v15, 0xffff0000, v24
	v_and_b32_e32 v14, 0xffff0000, v23
	v_pk_mul_f32 v[10:11], v[10:11], v[14:15]
	v_lshlrev_b32_e32 v12, 16, v17
	v_pk_mul_f32 v[10:11], v[10:11], v[10:11]
	s_nop 0
	v_pk_fma_f32 v[10:11], v[30:31], v[30:31], v[10:11]
	s_nop 0
	v_add_f32_e32 v1, v10, v1
	v_add_f32_e32 v1, v11, v1
	v_lshlrev_b32_e32 v10, 16, v13
	v_and_b32_e32 v11, 0xffff0000, v13
	v_and_b32_e32 v13, 0xffff0000, v17
	v_pk_add_f32 v[10:11], v[10:11], v[12:13]
	v_lshlrev_b32_e32 v12, 16, v25
	v_and_b32_e32 v13, 0xffff0000, v25
	v_pk_mul_f32 v[10:11], v[10:11], v[12:13]
	s_nop 0
	v_pk_mul_f32 v[10:11], v[10:11], v[10:11]
	s_nop 0
	v_add_f32_e32 v10, v10, v11
	v_add_f32_e32 v1, v10, v1
	s_waitcnt vmcnt(8)
	v_lshlrev_b32_e32 v30, 16, v48
	v_and_b32_e32 v31, 0xffff0000, v48
	s_waitcnt vmcnt(7)
	v_lshlrev_b32_e32 v32, 16, v52
	v_and_b32_e32 v33, 0xffff0000, v52
	v_pk_add_f32 v[30:31], v[30:31], v[32:33]
	s_waitcnt vmcnt(6)
	v_lshlrev_b32_e32 v32, 16, v56
	v_and_b32_e32 v33, 0xffff0000, v56
	v_pk_mul_f32 v[30:31], v[30:31], v[32:33]
	v_lshlrev_b32_e32 v33, 16, v54
	v_pk_mul_f32 v[30:31], v[30:31], v[30:31]
	v_lshlrev_b32_e32 v32, 16, v53
	v_add_f32_e32 v48, v30, v31
	v_lshlrev_b32_e32 v31, 16, v50
	v_lshlrev_b32_e32 v30, 16, v49
	v_pk_add_f32 v[30:31], v[30:31], v[32:33]
	v_lshlrev_b32_e32 v33, 16, v58
	v_lshlrev_b32_e32 v32, 16, v57
	v_add_f32_e32 v1, v1, v48
	v_pk_mul_f32 v[30:31], v[30:31], v[32:33]
	v_and_b32_e32 v33, 0xffff0000, v50
	v_and_b32_e32 v32, 0xffff0000, v49
	v_and_b32_e32 v49, 0xffff0000, v54
	v_and_b32_e32 v48, 0xffff0000, v53
	v_pk_add_f32 v[48:49], v[32:33], v[48:49]
	v_and_b32_e32 v53, 0xffff0000, v58
	v_and_b32_e32 v52, 0xffff0000, v57
	v_pk_mul_f32 v[48:49], v[48:49], v[52:53]
	v_lshlrev_b32_e32 v50, 16, v55
	v_pk_mul_f32 v[48:49], v[48:49], v[48:49]
	s_nop 0
	v_pk_fma_f32 v[48:49], v[30:31], v[30:31], v[48:49]
	s_nop 0
	v_add_f32_e32 v1, v48, v1
	v_add_f32_e32 v1, v49, v1
	v_lshlrev_b32_e32 v48, 16, v51
	v_and_b32_e32 v49, 0xffff0000, v51
	v_and_b32_e32 v51, 0xffff0000, v55
	v_pk_add_f32 v[48:49], v[48:49], v[50:51]
	v_lshlrev_b32_e32 v50, 16, v59
	v_and_b32_e32 v51, 0xffff0000, v59
	v_pk_mul_f32 v[48:49], v[48:49], v[50:51]
	s_nop 0
	v_pk_mul_f32 v[48:49], v[48:49], v[48:49]
	s_nop 0
	v_add_f32_e32 v48, v48, v49
	v_add_f32_e32 v1, v48, v1
	s_waitcnt vmcnt(5)
	v_lshlrev_b32_e32 v30, 16, v60
	v_and_b32_e32 v31, 0xffff0000, v60
	s_waitcnt vmcnt(4)
	v_lshlrev_b32_e32 v32, 16, v64
	v_and_b32_e32 v33, 0xffff0000, v64
	v_pk_add_f32 v[30:31], v[30:31], v[32:33]
	s_waitcnt vmcnt(3)
	v_lshlrev_b32_e32 v32, 16, v68
	v_and_b32_e32 v33, 0xffff0000, v68
	v_pk_mul_f32 v[30:31], v[30:31], v[32:33]
	v_lshlrev_b32_e32 v33, 16, v66
	v_pk_mul_f32 v[30:31], v[30:31], v[30:31]
	v_lshlrev_b32_e32 v32, 16, v65
	v_add_f32_e32 v60, v30, v31
	v_lshlrev_b32_e32 v31, 16, v62
	v_lshlrev_b32_e32 v30, 16, v61
	v_pk_add_f32 v[30:31], v[30:31], v[32:33]
	v_lshlrev_b32_e32 v33, 16, v70
	v_lshlrev_b32_e32 v32, 16, v69
	v_add_f32_e32 v1, v1, v60
	v_pk_mul_f32 v[30:31], v[30:31], v[32:33]
	v_and_b32_e32 v33, 0xffff0000, v62
	v_and_b32_e32 v32, 0xffff0000, v61
	v_and_b32_e32 v61, 0xffff0000, v66
	v_and_b32_e32 v60, 0xffff0000, v65
	v_pk_add_f32 v[60:61], v[32:33], v[60:61]
	v_and_b32_e32 v65, 0xffff0000, v70
	v_and_b32_e32 v64, 0xffff0000, v69
	v_pk_mul_f32 v[60:61], v[60:61], v[64:65]
	v_lshlrev_b32_e32 v62, 16, v67
	v_pk_mul_f32 v[60:61], v[60:61], v[60:61]
	s_nop 0
	v_pk_fma_f32 v[60:61], v[30:31], v[30:31], v[60:61]
	s_nop 0
	v_add_f32_e32 v1, v60, v1
	v_add_f32_e32 v1, v61, v1
	v_lshlrev_b32_e32 v60, 16, v63
	v_and_b32_e32 v61, 0xffff0000, v63
	v_and_b32_e32 v63, 0xffff0000, v67
	v_pk_add_f32 v[60:61], v[60:61], v[62:63]
	v_lshlrev_b32_e32 v62, 16, v71
	v_and_b32_e32 v63, 0xffff0000, v71
	v_pk_mul_f32 v[60:61], v[60:61], v[62:63]
	s_nop 0
	v_pk_mul_f32 v[60:61], v[60:61], v[60:61]
	s_nop 0
	v_add_f32_e32 v60, v60, v61
	v_add_f32_e32 v1, v60, v1
	s_waitcnt vmcnt(2)
; __device__ __forceinline__ void finish_phase(CParams& p, int layer) {
;     ...
; #pragma unroll 4
;             for (int kk = 0; kk < 16; ++kk) {
;                 const size_t off = base + (size_t)(g * 16 + kk) * 512;
;                 const u32x4 a = *(const u32x4*)(yf + off), bq = *(const u32x4*)(yb + off), zq = *(const u32x4*)(z + off);
;                 const unsigned aw[4] = {a.x, a.y, a.z, a.w}, bw[4] = {bq.x, bq.y, bq.z, bq.w}, zw[4] = {zq.x, zq.y, zq.z, zq.w};
; #pragma unroll
;                 for (int k = 0; k < 4; ++k) {
;                     const float v0 = (__uint_as_float(aw[k] << 16) + __uint_as_float(bw[k] << 16)) * __uint_as_float(zw[k] << 16);
;                     const float v1 = (__uint_as_float(aw[k] & 0xffff0000u) + __uint_as_float(bw[k] & 0xffff0000u)) * __uint_as_float(zw[k] & 0xffff0000u);
;                     ss += v0 * v0 + v1 * v1;
;                 }
;             }
;             ss += __shfl_xor(ss, 16); ss += __shfl_xor(ss, 32);
;             const float rstd = rsqrtf(ss * (1.f / 512.f) + EPS);
; #pragma unroll 4
;             for (int kk = 0; kk < 16; ++kk) {
;                 const size_t off = base + (size_t)(g * 16 + kk) * 512;
;                 const u32x4 a = *(const u32x4*)(yf + off), bq = *(const u32x4*)(yb + off), zq = *(const u32x4*)(z + off);
;                 const unsigned aw[4] = {a.x, a.y, a.z, a.w}, bw[4] = {bq.x, bq.y, bq.z, bq.w}, zw[4] = {zq.x, zq.y, zq.z, zq.w};
;                 const int col = (g * 16 + kk) * 32 + quad * 8;
;                 const f32x4 g0 = *(const f32x4*)(gn + col), g1 = *(const f32x4*)(gn + col + 4);
;                 const float gg[8] = {g0[0], g0[1], g0[2], g0[3], g1[0], g1[1], g1[2], g1[3]};
;                 unsigned ow[4];
; #pragma unroll
;                 for (int k = 0; k < 4; ++k) {
;                     const float v0 = (__uint_as_float(aw[k] << 16) + __uint_as_float(bw[k] << 16)) * __uint_as_float(zw[k] << 16);
;                     const float v1 = (__uint_as_float(aw[k] & 0xffff0000u) + __uint_as_float(bw[k] & 0xffff0000u)) * __uint_as_float(zw[k] & 0xffff0000u);
;                     ow[k] = pack2(v0 * rstd * gg[2 * k], v1 * rstd * gg[2 * k + 1]);
;                 }
;                 u32x4 o4; o4.x = ow[0]; o4.y = ow[1]; o4.z = ow[2]; o4.w = ow[3];
;                 *(u32x4*)(yf + off) = o4;
	v_lshlrev_b32_e32 v18, 16, v72
	v_and_b32_e32 v19, 0xffff0000, v72
	s_waitcnt vmcnt(1)
	v_lshlrev_b32_e32 v26, 16, v76
	v_and_b32_e32 v27, 0xffff0000, v76
	v_pk_add_f32 v[18:19], v[18:19], v[26:27]
	s_waitcnt vmcnt(0)
	v_lshlrev_b32_e32 v26, 16, v80
	v_and_b32_e32 v27, 0xffff0000, v80
	v_pk_mul_f32 v[18:19], v[18:19], v[26:27]
	v_lshlrev_b32_e32 v27, 16, v78
	v_pk_mul_f32 v[18:19], v[18:19], v[18:19]
	v_lshlrev_b32_e32 v26, 16, v77
	v_add_f32_e32 v72, v18, v19
	v_lshlrev_b32_e32 v19, 16, v74
	v_lshlrev_b32_e32 v18, 16, v73
	v_pk_add_f32 v[18:19], v[18:19], v[26:27]
	v_lshlrev_b32_e32 v27, 16, v82
	v_lshlrev_b32_e32 v26, 16, v81
	v_add_f32_e32 v1, v1, v72
	v_pk_mul_f32 v[18:19], v[18:19], v[26:27]
	v_and_b32_e32 v27, 0xffff0000, v74
	v_and_b32_e32 v26, 0xffff0000, v73
	v_and_b32_e32 v73, 0xffff0000, v78
	v_and_b32_e32 v72, 0xffff0000, v77
	v_pk_add_f32 v[72:73], v[26:27], v[72:73]
	v_and_b32_e32 v77, 0xffff0000, v82
	v_and_b32_e32 v76, 0xffff0000, v81
	v_pk_mul_f32 v[72:73], v[72:73], v[76:77]
	v_lshlrev_b32_e32 v74, 16, v79
	v_pk_mul_f32 v[72:73], v[72:73], v[72:73]
	s_nop 0
	v_pk_fma_f32 v[72:73], v[18:19], v[18:19], v[72:73]
	s_nop 0
	v_add_f32_e32 v1, v72, v1
	v_add_f32_e32 v1, v73, v1
	v_lshlrev_b32_e32 v72, 16, v75
	v_and_b32_e32 v73, 0xffff0000, v75
	v_and_b32_e32 v75, 0xffff0000, v79
	v_pk_add_f32 v[72:73], v[72:73], v[74:75]
	v_lshlrev_b32_e32 v74, 16, v83
	v_and_b32_e32 v75, 0xffff0000, v83
	v_pk_mul_f32 v[72:73], v[72:73], v[74:75]
	s_nop 0
	v_pk_mul_f32 v[72:73], v[72:73], v[72:73]
	s_nop 0
	v_add_f32_e32 v72, v72, v73
	v_add_f32_e32 v1, v72, v1
	s_cbranch_scc0 .LBB0_506
	ds_bpermute_b32 v10, v20, v1
	s_mov_b64 s[4:5], 0
	v_mov_b64_e32 v[12:13], v[8:9]
	s_waitcnt lgkmcnt(0)
	v_add_f32_e32 v1, v1, v10
	ds_bpermute_b32 v10, v21, v1
	s_waitcnt lgkmcnt(0)
	v_add_f32_e32 v1, v1, v10
	v_fmamk_f32 v1, v1, 0x3b000000, v166
	v_cmp_gt_f32_e32 vcc, s41, v1
	v_mul_f32_e32 v10, 0x4b800000, v1
	s_nop 0
	v_cndmask_b32_e32 v1, v1, v10, vcc
	v_rsq_f32_e32 v1, v1
	s_nop 0
	v_mul_f32_e32 v10, 0x45800000, v1
	v_cndmask_b32_e32 v10, v1, v10, vcc
	v_mov_b32_e32 v11, v10
.LBB0_508:
	s_nop 0
	v_lshl_add_u64 v[18:19], v[6:7], 0, s[4:5]
	v_add_co_u32_e32 v14, vcc, 0x2700000, v18
	s_add_u32 s4, s4, 0x1000
	s_nop 0
	v_addc_co_u32_e32 v15, vcc, 0, v19, vcc
	v_add_co_u32_e32 v16, vcc, 0x6900000, v18
	global_load_dwordx4 v[22:25], v[14:15], off
	s_nop 0
	v_addc_co_u32_e32 v17, vcc, 0, v19, vcc
	global_load_dwordx4 v[26:29], v[16:17], off
	v_add_co_u32_e32 v18, vcc, 0xab00000, v18
	s_addc_u32 s5, s5, 0
	s_nop 0
	v_addc_co_u32_e32 v19, vcc, 0, v19, vcc
	global_load_dwordx4 v[30:33], v[18:19], off
	global_load_dwordx4 v[34:37], v[12:13], off offset:-384
	global_load_dwordx4 v[38:41], v[12:13], off offset:-400
	global_load_dwordx4 v[48:51], v[14:15], off offset:1024
	global_load_dwordx4 v[52:55], v[16:17], off offset:1024
	global_load_dwordx4 v[56:59], v[18:19], off offset:1024
	global_load_dwordx4 v[60:63], v[12:13], off offset:-256
	global_load_dwordx4 v[64:67], v[12:13], off offset:-272
	global_load_dwordx4 v[68:71], v[14:15], off offset:2048
	global_load_dwordx4 v[72:75], v[16:17], off offset:2048
	global_load_dwordx4 v[76:79], v[18:19], off offset:2048
	global_load_dwordx4 v[80:83], v[12:13], off offset:-128
	global_load_dwordx4 v[84:87], v[12:13], off offset:-144
	s_mov_b64 s[8:9], 0x200
	s_cmpk_eq_i32 s4, 0x4000
	s_waitcnt vmcnt(14)
	v_lshlrev_b32_e32 v42, 16, v22
	v_and_b32_e32 v43, 0xffff0000, v22
	s_waitcnt vmcnt(13)
	v_lshlrev_b32_e32 v44, 16, v26
	v_and_b32_e32 v45, 0xffff0000, v26
	v_pk_add_f32 v[42:43], v[42:43], v[44:45]
	v_lshlrev_b32_e32 v26, 16, v27
	s_waitcnt vmcnt(12)
	v_lshlrev_b32_e32 v44, 16, v30
	v_and_b32_e32 v45, 0xffff0000, v30
	v_pk_mul_f32 v[42:43], v[42:43], v[44:45]
	v_and_b32_e32 v27, 0xffff0000, v27
	v_pk_mul_f32 v[42:43], v[10:11], v[42:43]
	v_lshlrev_b32_e32 v30, 16, v31
	s_waitcnt vmcnt(10)
	v_pk_mul_f32 v[38:39], v[38:39], v[42:43]
	v_and_b32_e32 v31, 0xffff0000, v31
	v_cvt_pk_bf16_f32 v22, v38, v39
	v_lshlrev_b32_e32 v38, 16, v23
	v_and_b32_e32 v39, 0xffff0000, v23
	v_pk_add_f32 v[26:27], v[38:39], v[26:27]
	s_nop 0
	v_pk_mul_f32 v[26:27], v[26:27], v[30:31]
	v_lshlrev_b32_e32 v30, 16, v28
	v_pk_mul_f32 v[26:27], v[10:11], v[26:27]
	v_and_b32_e32 v31, 0xffff0000, v28
	v_pk_mul_f32 v[26:27], v[40:41], v[26:27]
	v_lshlrev_b32_e32 v28, 16, v29
	v_cvt_pk_bf16_f32 v23, v26, v27
	v_lshlrev_b32_e32 v26, 16, v24
	v_and_b32_e32 v27, 0xffff0000, v24
	v_pk_add_f32 v[26:27], v[26:27], v[30:31]
	v_lshlrev_b32_e32 v30, 16, v32
	v_and_b32_e32 v31, 0xffff0000, v32
	v_pk_mul_f32 v[26:27], v[26:27], v[30:31]
	v_and_b32_e32 v29, 0xffff0000, v29
	v_pk_mul_f32 v[26:27], v[10:11], v[26:27]
	s_nop 0
	v_pk_mul_f32 v[26:27], v[34:35], v[26:27]
	s_nop 0
	v_cvt_pk_bf16_f32 v24, v26, v27
	v_lshlrev_b32_e32 v26, 16, v25
	v_and_b32_e32 v27, 0xffff0000, v25
	v_pk_add_f32 v[26:27], v[26:27], v[28:29]
	v_lshlrev_b32_e32 v28, 16, v33
	v_and_b32_e32 v29, 0xffff0000, v33
	v_pk_mul_f32 v[26:27], v[26:27], v[28:29]
	s_nop 0
	v_pk_mul_f32 v[26:27], v[10:11], v[26:27]
	s_nop 0
	v_pk_mul_f32 v[26:27], v[36:37], v[26:27]
	s_nop 0
	v_cvt_pk_bf16_f32 v25, v26, v27
	global_store_dwordx4 v[14:15], v[22:25], off
	s_waitcnt vmcnt(9)
	v_lshlrev_b32_e32 v42, 16, v48
	v_and_b32_e32 v43, 0xffff0000, v48
	s_waitcnt vmcnt(8)
	v_lshlrev_b32_e32 v44, 16, v52
	v_and_b32_e32 v45, 0xffff0000, v52
	v_pk_add_f32 v[42:43], v[42:43], v[44:45]
	s_waitcnt vmcnt(7)
	v_lshlrev_b32_e32 v44, 16, v56
	v_and_b32_e32 v45, 0xffff0000, v56
	v_pk_mul_f32 v[42:43], v[42:43], v[44:45]
	v_lshlrev_b32_e32 v52, 16, v53
	v_pk_mul_f32 v[42:43], v[10:11], v[42:43]
	v_and_b32_e32 v53, 0xffff0000, v53
	s_waitcnt vmcnt(5)
; __device__ __forceinline__ unsigned pack2(float a, float b) { const f32v2_t v = {a, b}; return __builtin_bit_cast(unsigned, __builtin_convertvector(v, bf16v2_t)); }
; __device__ __forceinline__ void finish_phase(CParams& p, int layer) {
;     ...
; #pragma unroll 4
;             for (int kk = 0; kk < 16; ++kk) {
;                 const size_t off = base + (size_t)(g * 16 + kk) * 512;
;                 const u32x4 a = *(const u32x4*)(yf + off), bq = *(const u32x4*)(yb + off), zq = *(const u32x4*)(z + off);
;                 const unsigned aw[4] = {a.x, a.y, a.z, a.w}, bw[4] = {bq.x, bq.y, bq.z, bq.w}, zw[4] = {zq.x, zq.y, zq.z, zq.w};
;                 const int col = (g * 16 + kk) * 32 + quad * 8;
;                 const f32x4 g0 = *(const f32x4*)(gn + col), g1 = *(const f32x4*)(gn + col + 4);
;                 const float gg[8] = {g0[0], g0[1], g0[2], g0[3], g1[0], g1[1], g1[2], g1[3]};
;                 unsigned ow[4];
; #pragma unroll
;                 for (int k = 0; k < 4; ++k) {
;                     const float v0 = (__uint_as_float(aw[k] << 16) + __uint_as_float(bw[k] << 16)) * __uint_as_float(zw[k] << 16);
;                     const float v1 = (__uint_as_float(aw[k] & 0xffff0000u) + __uint_as_float(bw[k] & 0xffff0000u)) * __uint_as_float(zw[k] & 0xffff0000u);
;                     ow[k] = pack2(v0 * rstd * gg[2 * k], v1 * rstd * gg[2 * k + 1]);
;                 }
;                 u32x4 o4; o4.x = ow[0]; o4.y = ow[1]; o4.z = ow[2]; o4.w = ow[3];
;                 *(u32x4*)(yf + off) = o4;
;             }
;         }
;     }
	v_pk_mul_f32 v[64:65], v[64:65], v[42:43]
	v_lshlrev_b32_e32 v56, 16, v57
	v_cvt_pk_bf16_f32 v48, v64, v65
	v_lshlrev_b32_e32 v64, 16, v49
	v_and_b32_e32 v65, 0xffff0000, v49
	v_pk_add_f32 v[52:53], v[64:65], v[52:53]
	v_and_b32_e32 v57, 0xffff0000, v57
	v_pk_mul_f32 v[52:53], v[52:53], v[56:57]
	v_lshlrev_b32_e32 v56, 16, v54
	v_pk_mul_f32 v[52:53], v[10:11], v[52:53]
	v_and_b32_e32 v57, 0xffff0000, v54
	v_pk_mul_f32 v[52:53], v[66:67], v[52:53]
	v_lshlrev_b32_e32 v54, 16, v55
	v_cvt_pk_bf16_f32 v49, v52, v53
	v_lshlrev_b32_e32 v52, 16, v50
	v_and_b32_e32 v53, 0xffff0000, v50
	v_pk_add_f32 v[52:53], v[52:53], v[56:57]
	v_lshlrev_b32_e32 v56, 16, v58
	v_and_b32_e32 v57, 0xffff0000, v58
	v_pk_mul_f32 v[52:53], v[52:53], v[56:57]
	v_and_b32_e32 v55, 0xffff0000, v55
	v_pk_mul_f32 v[52:53], v[10:11], v[52:53]
	s_nop 0
	v_pk_mul_f32 v[52:53], v[60:61], v[52:53]
	s_nop 0
	v_cvt_pk_bf16_f32 v50, v52, v53
	v_lshlrev_b32_e32 v52, 16, v51
	v_and_b32_e32 v53, 0xffff0000, v51
	v_pk_add_f32 v[52:53], v[52:53], v[54:55]
	v_lshlrev_b32_e32 v54, 16, v59
	v_and_b32_e32 v55, 0xffff0000, v59
	v_pk_mul_f32 v[52:53], v[52:53], v[54:55]
	s_nop 0
	v_pk_mul_f32 v[52:53], v[10:11], v[52:53]
	s_nop 0
	v_pk_mul_f32 v[52:53], v[62:63], v[52:53]
	s_nop 0
	v_cvt_pk_bf16_f32 v51, v52, v53
	global_store_dwordx4 v[14:15], v[48:51], off offset:1024
	s_waitcnt vmcnt(4)
	v_lshlrev_b32_e32 v42, 16, v68
	v_and_b32_e32 v43, 0xffff0000, v68
	s_waitcnt vmcnt(3)
	v_lshlrev_b32_e32 v44, 16, v72
	v_and_b32_e32 v45, 0xffff0000, v72
	v_pk_add_f32 v[42:43], v[42:43], v[44:45]
	s_waitcnt vmcnt(2)
	v_lshlrev_b32_e32 v44, 16, v76
	v_and_b32_e32 v45, 0xffff0000, v76
	v_pk_mul_f32 v[42:43], v[42:43], v[44:45]
	v_lshlrev_b32_e32 v72, 16, v73
	v_pk_mul_f32 v[42:43], v[10:11], v[42:43]
	v_and_b32_e32 v73, 0xffff0000, v73
	s_waitcnt vmcnt(0)
	v_pk_mul_f32 v[84:85], v[84:85], v[42:43]
	v_lshlrev_b32_e32 v76, 16, v77
	v_cvt_pk_bf16_f32 v68, v84, v85
	v_lshlrev_b32_e32 v84, 16, v69
	v_and_b32_e32 v85, 0xffff0000, v69
	v_pk_add_f32 v[72:73], v[84:85], v[72:73]
	v_and_b32_e32 v77, 0xffff0000, v77
	v_pk_mul_f32 v[72:73], v[72:73], v[76:77]
	v_lshlrev_b32_e32 v76, 16, v74
	v_pk_mul_f32 v[72:73], v[10:11], v[72:73]
	v_and_b32_e32 v77, 0xffff0000, v74
	v_pk_mul_f32 v[72:73], v[86:87], v[72:73]
	v_lshlrev_b32_e32 v74, 16, v75
	v_cvt_pk_bf16_f32 v69, v72, v73
	v_lshlrev_b32_e32 v72, 16, v70
	v_and_b32_e32 v73, 0xffff0000, v70
	v_pk_add_f32 v[72:73], v[72:73], v[76:77]
	v_lshlrev_b32_e32 v76, 16, v78
	v_and_b32_e32 v77, 0xffff0000, v78
	v_pk_mul_f32 v[72:73], v[72:73], v[76:77]
	v_and_b32_e32 v75, 0xffff0000, v75
	v_pk_mul_f32 v[72:73], v[10:11], v[72:73]
	s_nop 0
	v_pk_mul_f32 v[72:73], v[80:81], v[72:73]
	s_nop 0
	v_cvt_pk_bf16_f32 v70, v72, v73
	v_lshlrev_b32_e32 v72, 16, v71
	v_and_b32_e32 v73, 0xffff0000, v71
	v_pk_add_f32 v[72:73], v[72:73], v[74:75]
	v_lshlrev_b32_e32 v74, 16, v79
	v_and_b32_e32 v75, 0xffff0000, v79
	v_pk_mul_f32 v[72:73], v[72:73], v[74:75]
	s_nop 0
	v_pk_mul_f32 v[72:73], v[10:11], v[72:73]
	s_nop 0
	v_pk_mul_f32 v[72:73], v[82:83], v[72:73]
	s_nop 0
	v_cvt_pk_bf16_f32 v71, v72, v73
	global_store_dwordx4 v[14:15], v[68:71], off offset:2048
	global_load_dwordx4 v[22:25], v[14:15], off offset:3072
	s_nop 0
	global_load_dwordx4 v[26:29], v[16:17], off offset:3072
	s_nop 0
	global_load_dwordx4 v[16:19], v[18:19], off offset:3072
	s_nop 0
	global_load_dwordx4 v[30:33], v[12:13], off
	global_load_dwordx4 v[34:37], v[12:13], off offset:-16
	v_lshl_add_u64 v[12:13], v[12:13], 0, s[8:9]
	s_waitcnt vmcnt(4)
	v_lshlrev_b32_e32 v38, 16, v22
	v_and_b32_e32 v39, 0xffff0000, v22
	s_waitcnt vmcnt(3)
	v_lshlrev_b32_e32 v40, 16, v26
	v_and_b32_e32 v41, 0xffff0000, v26
	v_lshlrev_b32_e32 v22, 16, v23
	v_and_b32_e32 v23, 0xffff0000, v23
	v_lshlrev_b32_e32 v26, 16, v27
	v_and_b32_e32 v27, 0xffff0000, v27
	v_pk_add_f32 v[22:23], v[22:23], v[26:27]
	s_waitcnt vmcnt(2)
	v_lshlrev_b32_e32 v26, 16, v17
	v_and_b32_e32 v27, 0xffff0000, v17
	v_pk_mul_f32 v[22:23], v[22:23], v[26:27]
	v_lshlrev_b32_e32 v26, 16, v28
	v_pk_mul_f32 v[22:23], v[10:11], v[22:23]
	v_and_b32_e32 v27, 0xffff0000, v28
	s_waitcnt vmcnt(0)
	v_pk_mul_f32 v[22:23], v[36:37], v[22:23]
	v_pk_add_f32 v[38:39], v[38:39], v[40:41]
	v_cvt_pk_bf16_f32 v17, v22, v23
	v_lshlrev_b32_e32 v22, 16, v24
	v_and_b32_e32 v23, 0xffff0000, v24
	v_pk_add_f32 v[22:23], v[22:23], v[26:27]
	v_lshlrev_b32_e32 v26, 16, v18
	v_and_b32_e32 v27, 0xffff0000, v18
	v_pk_mul_f32 v[22:23], v[22:23], v[26:27]
	v_lshlrev_b32_e32 v24, 16, v29
	v_pk_mul_f32 v[22:23], v[10:11], v[22:23]
	v_lshlrev_b32_e32 v40, 16, v16
	v_pk_mul_f32 v[22:23], v[30:31], v[22:23]
	v_and_b32_e32 v41, 0xffff0000, v16
	v_cvt_pk_bf16_f32 v18, v22, v23
	v_lshlrev_b32_e32 v22, 16, v25
	v_and_b32_e32 v23, 0xffff0000, v25
	v_and_b32_e32 v25, 0xffff0000, v29
	v_pk_add_f32 v[22:23], v[22:23], v[24:25]
	v_lshlrev_b32_e32 v24, 16, v19
	v_and_b32_e32 v25, 0xffff0000, v19
	v_pk_mul_f32 v[38:39], v[38:39], v[40:41]
	v_pk_mul_f32 v[22:23], v[22:23], v[24:25]
	v_pk_mul_f32 v[38:39], v[10:11], v[38:39]
	v_pk_mul_f32 v[22:23], v[10:11], v[22:23]
	v_pk_mul_f32 v[34:35], v[34:35], v[38:39]
	v_pk_mul_f32 v[22:23], v[32:33], v[22:23]
	v_cvt_pk_bf16_f32 v16, v34, v35
	v_cvt_pk_bf16_f32 v19, v22, v23
	global_store_dwordx4 v[14:15], v[16:19], off offset:3072
	s_cbranch_scc0 .LBB0_508
	s_mov_b64 s[4:5], 0x4000
	s_add_i32 s6, s6, 1
	v_lshl_add_u64 v[6:7], v[6:7], 0, s[4:5]
	s_mov_b64 s[4:5], 0x800
	s_cmp_eq_u32 s6, 4
	v_lshl_add_u64 v[8:9], v[8:9], 0, s[4:5]
	s_cbranch_scc0 .LBB0_505
	v_add_u32_e32 v0, s54, v0
	s_movk_i32 s4, 0x41f
	v_cmp_lt_i32_e32 vcc, s4, v0
	s_or_b64 s[44:45], vcc, s[44:45]
	s_andn2_b64 exec, exec, s[44:45]
	s_cbranch_execnz .LBB0_504
